# attnA: K chunk c+1 staged through LDS while chunk c's MFMAs run (run 1)
# baseline (speedup 1.0000x reference)
; #define GAS __attribute__((address_space(1)))
; __device__ __forceinline__ void attnA_unit(const Ctx& C, int unit) {
;     ...
;         const int tq = r + dl * (i0 + i16);
;         const unsigned qoff = (unsigned)tq * (ZC * 2) + (QA + head * 64 + 8 * g) * 2;
;         const bf16x8 q0 = *(const GAS bf16x8*)(Zg + qoff), q1 = *(const GAS bf16x8*)(Zg + qoff + 64);
;         const int kbase = i0 - 144;
;         const int klane = kbase + 8 * (i16 >> 2) + (i16 & 3);
;         const unsigned kcol = rbase + (KA + head * 64 + 8 * g) * 2;
;         bf16x8 kf[10][2];
; #pragma unroll
;         for (int kt = 0; kt < 10; ++kt) { int ks = klane + 32 * (kt >> 1) + 4 * (kt & 1); ks = ks < 0 ? 0 : ks;
;             const unsigned off = (unsigned)ks * rstride + kcol; kf[kt][0] = *(const GAS bf16x8*)(Zg + off); kf[kt][1] = *(const GAS bf16x8*)(Zg + off + 64); }
;         v4u vreg[5][4];
;         { const int vl = kbase + (lane >> 3); const unsigned vcol = rbase + (VA + head * 64 + (lane & 7) * 8) * 2;
; #pragma unroll
;           for (int s5 = 0; s5 < 5; ++s5)
; #pragma unroll
;             for (int i = 0; i < 4; ++i) { int ks = vl + 32 * s5 + 8 * i; ks = ks < 0 ? 0 : ks; vreg[s5][i] = *(const GAS v4u*)(Zg + (unsigned)ks * rstride + vcol); } }
.LBB0_565:
	v_add_u32_e32 v0, s24, v133
	v_mul_lo_u32 v0, s25, v0
	s_lshl_b32 s68, s26, 8
	v_add_u32_e32 v145, s56, v0
	s_or_b32 s31, s68, s36
	v_mul_lo_u32 v0, v145, s33
	v_or_b32_e32 v1, s31, v134
	s_mul_i32 s27, s25, 0x2600
	v_lshl_add_u32 v0, v1, 1, v0
	s_add_i32 s25, s24, 0xffffff70
	s_mul_i32 s30, s56, 0x2600
	v_add_u32_e32 v2, s24, v139
	v_mul_lo_u32 v2, v2, s27
	v_add_u32_e32 v2, s30, v2
	v_and_b32_e32 v3, 0x70, v140
	v_add_u32_e32 v2, v2, v3
	s_lshl_b32 s28, s31, 1
	v_add_u32_e32 v2, s28, v2
	s_lshl_b32 s28, s27, 3
	global_load_dwordx4 v[84:87], v2, s[66:67]
	v_add_u32_e32 v3, s28, v2
	global_load_dwordx4 v[80:83], v3, s[66:67]
	s_lshl_b32 s28, s31, 1
	v_add_u32_e32 v12, s25, v139
	s_add_i32 s30, s30, s28
	v_add_u32_e32 v192, s30, v140
	v_lshl_add_u64 v[8:9], s[66:67], 0, v[192:193]
	v_max_i32_e32 v0, 0, v12
	v_mul_lo_u32 v192, v0, s27
	v_lshl_add_u64 v[0:1], v[8:9], 0, v[192:193]
	global_load_dwordx4 v[146:149], v[0:1], off offset:-1536
	v_max_i32_e32 v2, -8, v12
	v_add_u32_e32 v2, 8, v2
	v_mul_lo_u32 v192, v2, s27
	v_lshl_add_u64 v[2:3], v[8:9], 0, v[192:193]
	global_load_dwordx4 v[150:153], v[2:3], off offset:-1536
	v_max_i32_e32 v0, -16, v12
	v_add_u32_e32 v0, 16, v0
	v_mul_lo_u32 v192, v0, s27
	v_lshl_add_u64 v[0:1], v[8:9], 0, v[192:193]
	global_load_dwordx4 v[154:157], v[0:1], off offset:-1536
	v_max_i32_e32 v2, -24, v12
	v_add_u32_e32 v2, 24, v2
	v_mul_lo_u32 v192, v2, s27
	v_lshl_add_u64 v[2:3], v[8:9], 0, v[192:193]
	global_load_dwordx4 v[158:161], v[2:3], off offset:-1536
	v_max_i32_e32 v0, -32, v12
	v_add_u32_e32 v0, 32, v0
	v_mul_lo_u32 v192, v0, s27
	v_lshl_add_u64 v[0:1], v[8:9], 0, v[192:193]
	global_load_dwordx4 v[162:165], v[0:1], off offset:-1536
	v_max_i32_e32 v2, -40, v12
	v_add_u32_e32 v2, 40, v2
	v_mul_lo_u32 v192, v2, s27
	v_lshl_add_u64 v[2:3], v[8:9], 0, v[192:193]
	global_load_dwordx4 v[166:169], v[2:3], off offset:-1536
	v_max_i32_e32 v0, -48, v12
	v_add_u32_e32 v0, 48, v0
	v_mul_lo_u32 v192, v0, s27
	v_lshl_add_u64 v[0:1], v[8:9], 0, v[192:193]
	global_load_dwordx4 v[170:173], v[0:1], off offset:-1536
	v_max_i32_e32 v2, -56, v12
	v_add_u32_e32 v2, 56, v2
	v_mul_lo_u32 v192, v2, s27
	v_lshl_add_u64 v[2:3], v[8:9], 0, v[192:193]
	global_load_dwordx4 v[174:177], v[2:3], off offset:-1536
	v_max_i32_e32 v0, -64, v12
	v_add_u32_e32 v0, 64, v0
	v_mul_lo_u32 v192, v0, s27
	v_lshl_add_u64 v[0:1], v[8:9], 0, v[192:193]
	global_load_dwordx4 v[178:181], v[0:1], off offset:-1536
	v_max_i32_e32 v2, -72, v12
	v_add_u32_e32 v2, 72, v2
	v_mul_lo_u32 v192, v2, s27
	v_lshl_add_u64 v[2:3], v[8:9], 0, v[192:193]
	global_load_dwordx4 v[128:131], v[2:3], off offset:-1536
	v_max_i32_e32 v0, -80, v12
	v_add_u32_e32 v0, 80, v0
	v_mul_lo_u32 v192, v0, s27
	v_lshl_add_u64 v[0:1], v[8:9], 0, v[192:193]
	global_load_dwordx4 v[124:127], v[0:1], off offset:-1536
	v_max_i32_e32 v2, -88, v12
	v_add_u32_e32 v2, 88, v2
	v_mul_lo_u32 v192, v2, s27
	v_lshl_add_u64 v[2:3], v[8:9], 0, v[192:193]
	global_load_dwordx4 v[120:123], v[2:3], off offset:-1536
	v_max_i32_e32 v0, -96, v12
	v_add_u32_e32 v0, 96, v0
	v_mul_lo_u32 v192, v0, s27
	v_lshl_add_u64 v[0:1], v[8:9], 0, v[192:193]
	global_load_dwordx4 v[116:119], v[0:1], off offset:-1536
	v_max_i32_e32 v2, -104, v12
	v_add_u32_e32 v2, 104, v2
	v_mul_lo_u32 v192, v2, s27
	v_lshl_add_u64 v[2:3], v[8:9], 0, v[192:193]
	global_load_dwordx4 v[112:115], v[2:3], off offset:-1536
	v_max_i32_e32 v0, -112, v12
	v_add_u32_e32 v0, 112, v0
	v_mul_lo_u32 v192, v0, s27
	v_lshl_add_u64 v[0:1], v[8:9], 0, v[192:193]
	global_load_dwordx4 v[108:111], v[0:1], off offset:-1536
	v_max_i32_e32 v2, -120, v12
	v_add_u32_e32 v2, 120, v2
	v_mul_lo_u32 v192, v2, s27
	v_lshl_add_u64 v[2:3], v[8:9], 0, v[192:193]
	global_load_dwordx4 v[100:103], v[2:3], off offset:-1536
	v_max_i32_e32 v0, -128, v12
	v_add_u32_e32 v0, 128, v0
	v_mul_lo_u32 v192, v0, s27
	v_lshl_add_u64 v[0:1], v[8:9], 0, v[192:193]
	global_load_dwordx4 v[104:107], v[0:1], off offset:-1536
	v_max_i32_e32 v2, -136, v12
	v_add_u32_e32 v2, 136, v2
	v_mul_lo_u32 v192, v2, s27
	v_lshl_add_u64 v[2:3], v[8:9], 0, v[192:193]
	global_load_dwordx4 v[96:99], v[2:3], off offset:-1536
	v_max_i32_e32 v0, -144, v12
	v_add_u32_e32 v0, 144, v0
	v_mul_lo_u32 v192, v0, s27
	v_lshl_add_u64 v[0:1], v[8:9], 0, v[192:193]
	global_load_dwordx4 v[92:95], v[0:1], off offset:-1536
	v_max_i32_e32 v2, -152, v12
	v_add_u32_e32 v2, 152, v2
	v_mul_lo_u32 v192, v2, s27
	v_lshl_add_u64 v[2:3], v[8:9], 0, v[192:193]
	global_load_dwordx4 v[88:91], v[2:3], off offset:-1536
	v_add_u32_e32 v192, s30, v140
	v_max_i32_e32 v0, 0, v12
	v_max_i32_e32 v2, -8, v12
	v_lshl_add_u64 v[8:9], s[66:67], 0, v[192:193]
	v_mul_lo_u32 v192, v0, s27
	v_add_u32_e32 v2, 8, v2
	v_lshl_add_u64 v[0:1], v[8:9], 0, v[192:193]
	v_mul_lo_u32 v192, v2, s27
	v_lshl_add_u64 v[2:3], v[8:9], 0, v[192:193]
	global_load_dwordx4 v[64:67], v[0:1], off
	global_load_dwordx4 v[68:71], v[2:3], off
	v_max_i32_e32 v0, -16, v12
	v_add_u32_e32 v0, 16, v0
	v_max_i32_e32 v2, 0xffffffe8, v12
	v_mul_lo_u32 v192, v0, s27
	v_add_u32_e32 v2, 24, v2
	v_lshl_add_u64 v[0:1], v[8:9], 0, v[192:193]
	v_mul_lo_u32 v192, v2, s27
	v_lshl_add_u64 v[2:3], v[8:9], 0, v[192:193]
	global_load_dwordx4 v[72:75], v[0:1], off
	global_load_dwordx4 v[76:79], v[2:3], off
	v_max_i32_e32 v0, 0xffffffe0, v12
	v_add_u32_e32 v0, 32, v0
	v_max_i32_e32 v2, 0xffffffd8, v12
	v_mul_lo_u32 v192, v0, s27
	v_add_u32_e32 v2, 40, v2
	v_lshl_add_u64 v[0:1], v[8:9], 0, v[192:193]
	v_mul_lo_u32 v192, v2, s27
	v_lshl_add_u64 v[2:3], v[8:9], 0, v[192:193]
	global_load_dwordx4 v[48:51], v[0:1], off
	global_load_dwordx4 v[52:55], v[2:3], off
	v_max_i32_e32 v0, 0xffffffd0, v12
; #define GAS __attribute__((address_space(1)))
; __device__ __forceinline__ f32x4 mfma16(bf16x8 a, bf16x8 b, f32x4 c) { return __builtin_amdgcn_mfma_f32_16x16x32_bf16(a, b, c, 0, 0, 0); }
; #define SBAR() __builtin_amdgcn_sched_barrier(0)
; #define SBAR() __builtin_amdgcn_sched_barrier(0)
; __device__ __forceinline__ void attnA_unit(const Ctx& C, int unit) {
;     ...
; #pragma unroll
;         for (int kt = 0; kt < 10; ++kt) { int ks = klane + 32 * (kt >> 1) + 4 * (kt & 1); ks = ks < 0 ? 0 : ks;
;             const unsigned off = (unsigned)ks * rstride + kcol; kf[kt][0] = *(const GAS bf16x8*)(Zg + off); kf[kt][1] = *(const GAS bf16x8*)(Zg + off + 64); }
;         v4u vreg[5][4];
;         { const int vl = kbase + (lane >> 3); const unsigned vcol = rbase + (VA + head * 64 + (lane & 7) * 8) * 2;
; #pragma unroll
;           for (int s5 = 0; s5 < 5; ++s5)
; #pragma unroll
;             for (int i = 0; i < 4; ++i) { int ks = vl + 32 * s5 + 8 * i; ks = ks < 0 ? 0 : ks; vreg[s5][i] = *(const GAS v4u*)(Zg + (unsigned)ks * rstride + vcol); } }
;         SBAR();
;         f32x4 S[10];
; #pragma unroll
;         for (int kt = 0; kt < 10; ++kt) { f32x4 a = mfma16(kf[kt][0], q0, (f32x4){0.f, 0.f, 0.f, 0.f}); S[kt] = mfma16(kf[kt][1], q1, a); }
	v_add_u32_e32 v0, 48, v0
	v_max_i32_e32 v2, 0xffffffc8, v12
	v_mul_lo_u32 v192, v0, s27
	v_add_u32_e32 v2, 56, v2
	v_lshl_add_u64 v[0:1], v[8:9], 0, v[192:193]
	v_mul_lo_u32 v192, v2, s27
	v_lshl_add_u64 v[2:3], v[8:9], 0, v[192:193]
	global_load_dwordx4 v[56:59], v[0:1], off
	global_load_dwordx4 v[60:63], v[2:3], off
	v_max_i32_e32 v0, 0xffffffc0, v12
	v_add_u32_e32 v0, 64, v0
	v_max_i32_e32 v2, 0xffffffb8, v12
	v_mul_lo_u32 v192, v0, s27
	v_add_u32_e32 v2, 0x48, v2
	v_lshl_add_u64 v[0:1], v[8:9], 0, v[192:193]
	v_mul_lo_u32 v192, v2, s27
	v_lshl_add_u64 v[2:3], v[8:9], 0, v[192:193]
	global_load_dwordx4 v[32:35], v[0:1], off
	global_load_dwordx4 v[36:39], v[2:3], off
	v_max_i32_e32 v0, 0xffffffb0, v12
	v_add_u32_e32 v0, 0x50, v0
	v_max_i32_e32 v2, 0xffffffa8, v12
	v_mul_lo_u32 v192, v0, s27
	v_add_u32_e32 v2, 0x58, v2
	v_lshl_add_u64 v[0:1], v[8:9], 0, v[192:193]
	v_mul_lo_u32 v192, v2, s27
	v_lshl_add_u64 v[2:3], v[8:9], 0, v[192:193]
	global_load_dwordx4 v[40:43], v[0:1], off
	global_load_dwordx4 v[44:47], v[2:3], off
	v_max_i32_e32 v0, 0xffffffa0, v12
	v_add_u32_e32 v0, 0x60, v0
	v_max_i32_e32 v2, 0xffffff98, v12
	v_mul_lo_u32 v192, v0, s27
	v_add_u32_e32 v2, 0x68, v2
	v_lshl_add_u64 v[0:1], v[8:9], 0, v[192:193]
	v_mul_lo_u32 v192, v2, s27
	v_lshl_add_u64 v[2:3], v[8:9], 0, v[192:193]
	global_load_dwordx4 v[16:19], v[0:1], off
	global_load_dwordx4 v[20:23], v[2:3], off
	v_max_i32_e32 v0, 0xffffff90, v12
	v_add_u32_e32 v0, 0x70, v0
	v_max_i32_e32 v2, 0xffffff88, v12
	v_mul_lo_u32 v192, v0, s27
	v_add_u32_e32 v2, 0x78, v2
	v_lshl_add_u64 v[0:1], v[8:9], 0, v[192:193]
	v_mul_lo_u32 v192, v2, s27
	v_lshl_add_u64 v[2:3], v[8:9], 0, v[192:193]
	global_load_dwordx4 v[24:27], v[0:1], off
	global_load_dwordx4 v[28:31], v[2:3], off
	v_max_i32_e32 v0, 0xffffff80, v12
	v_add_u32_e32 v0, 0x80, v0
	v_max_i32_e32 v2, 0xffffff78, v12
	v_mul_lo_u32 v192, v0, s27
	v_add_u32_e32 v2, 0x88, v2
	v_add_u32_e32 v10, s24, v139
	v_lshl_add_u64 v[0:1], v[8:9], 0, v[192:193]
	v_mul_lo_u32 v192, v2, s27
	v_max_i32_e32 v10, 0, v10
	v_max_i32_e32 v12, 0xffffff68, v12
	v_lshl_add_u64 v[4:5], v[8:9], 0, v[192:193]
	v_mul_lo_u32 v192, s27, v10
	v_add_u32_e32 v12, 0x98, v12
	v_lshl_add_u64 v[10:11], v[8:9], 0, v[192:193]
	v_mul_lo_u32 v192, v12, s27
	v_lshl_add_u64 v[12:13], v[8:9], 0, v[192:193]
	global_load_dwordx4 v[0:3], v[0:1], off
	s_nop 0
	global_load_dwordx4 v[4:7], v[4:5], off
	s_nop 0
	global_load_dwordx4 v[8:11], v[10:11], off
	s_nop 0
	global_load_dwordx4 v[12:15], v[12:13], off
	s_waitcnt vmcnt(32)
	ds_write_b128 v143, v[84:87] offset:2240
	ds_write_b128 v143, v[80:83] offset:3392
	ds_read_b128 v[84:87], v207 offset:2240
	ds_read_b128 v[80:83], v207 offset:2304
	ds_write_b128 v206, v[146:149] offset:2240
	ds_write_b128 v206, v[150:153] offset:2816
	ds_write_b128 v206, v[154:157] offset:3392
	ds_write_b128 v206, v[158:161] offset:3968
	ds_read_b128 v[146:149], v207 offset:2240
	ds_read_b128 v[150:153], v207 offset:2304
	ds_read_b128 v[154:157], v207 offset:4544
	ds_read_b128 v[158:161], v207 offset:4608
	ds_write_b128 v206, v[162:165] offset:2240
	ds_write_b128 v206, v[166:169] offset:2816
	ds_write_b128 v206, v[170:173] offset:3392
	ds_write_b128 v206, v[174:177] offset:3968
	ds_read_b128 v[162:165], v207 offset:2240
	ds_read_b128 v[166:169], v207 offset:2304
	ds_read_b128 v[170:173], v207 offset:4544
	ds_read_b128 v[174:177], v207 offset:4608
	s_waitcnt lgkmcnt(8)
	s_waitcnt vmcnt(39)
	v_mfma_f32_16x16x32_bf16 v[146:149], v[146:149], v[84:87], 0
	s_mulk_i32 s26, 0x2c0
	v_add_u32_e32 v186, s26, v135
	ds_read2_b32 v[182:183], v186 offset0:173 offset1:176
	s_waitcnt vmcnt(38)
	v_mfma_f32_16x16x32_bf16 v[146:149], v[150:153], v[80:83], v[146:149]
	s_waitcnt vmcnt(37)
	v_mfma_f32_16x16x32_bf16 v[150:153], v[154:157], v[84:87], 0
	s_waitcnt vmcnt(36)
	v_mfma_f32_16x16x32_bf16 v[154:157], v[158:161], v[80:83], v[150:153]
	s_waitcnt lgkmcnt(0)
	s_nop 2
	v_fmamk_f32 v146, v146, 0x3e000000, v183
	v_fmac_f32_e32 v182, 0x3e000000, v149
	v_cndmask_b32_e64 v146, v237, v146, s[38:39]
	s_waitcnt vmcnt(28)
	ds_write_b128 v206, v[178:181] offset:2240
	ds_write_b128 v206, v[128:131] offset:2816
	ds_write_b128 v206, v[124:127] offset:3392
	ds_write_b128 v206, v[120:123] offset:3968
	ds_read_b128 v[178:181], v207 offset:2240
	ds_read_b128 v[128:131], v207 offset:2304
	ds_read_b128 v[124:127], v207 offset:4544
	ds_read_b128 v[120:123], v207 offset:4608
	s_waitcnt lgkmcnt(8)
	s_waitcnt vmcnt(35)
	v_mfma_f32_16x16x32_bf16 v[150:153], v[162:165], v[84:87], 0
	ds_read2_b32 v[162:163], v186 offset0:174 offset1:175
	v_mov_b32_e32 v164, v147
	v_mov_b32_e32 v165, v148
	s_waitcnt vmcnt(34)
	v_mfma_f32_16x16x32_bf16 v[158:161], v[166:169], v[80:83], v[150:153]
	ds_read2_b32 v[184:185], v186 offset0:169 offset1:170
	s_nop 1
	ds_read2_b32 v[150:151], v186 offset0:171 offset1:172
	s_waitcnt lgkmcnt(2)
	v_pk_fma_f32 v[152:153], v[164:165], s[80:81], v[162:163] op_sel:[0,0,1] op_sel_hi:[1,0,0]
	v_cndmask_b32_e64 v149, v237, v182, s[46:47]
	s_waitcnt vmcnt(33)
	v_mfma_f32_16x16x32_bf16 v[162:165], v[170:173], v[84:87], 0
	s_waitcnt lgkmcnt(1)
	v_fmac_f32_e32 v184, 0x3e000000, v157
	s_waitcnt lgkmcnt(0)
	v_pk_fma_f32 v[150:151], v[154:155], s[80:81], v[150:151] op_sel:[0,0,1] op_sel_hi:[1,0,0]
	v_cndmask_b32_e64 v147, v237, v153, s[40:41]
	s_waitcnt vmcnt(24)
	ds_write_b128 v206, v[116:119] offset:2240
	ds_write_b128 v206, v[112:115] offset:2816
	ds_write_b128 v206, v[108:111] offset:3392
	ds_write_b128 v206, v[100:103] offset:3968
	ds_read_b128 v[116:119], v207 offset:2240
	ds_read_b128 v[112:115], v207 offset:2304
	ds_read_b128 v[108:111], v207 offset:4544
	ds_read_b128 v[100:103], v207 offset:4608
	s_waitcnt lgkmcnt(8)
; #define LAS __attribute__((address_space(3)))
; __device__ __forceinline__ f32x4 mfma16(bf16x8 a, bf16x8 b, f32x4 c) { return __builtin_amdgcn_mfma_f32_16x16x32_bf16(a, b, c, 0, 0, 0); }
; #define SBAR() __builtin_amdgcn_sched_barrier(0)
; #define SBAR() __builtin_amdgcn_sched_barrier(0)
; __device__ __forceinline__ void attnA_unit(const Ctx& C, int unit) {
;     ...
;         for (int kt = 0; kt < 10; ++kt) { f32x4 a = mfma16(kf[kt][0], q0, (f32x4){0.f, 0.f, 0.f, 0.f}); S[kt] = mfma16(kf[kt][1], q1, a); }
;         const LAS float* tb = biasT + grp * 176 + 16 + L - 159;
;         const int kneg = kbase + 8 * g;
;         const bool anyneg = kbase < 0;
;         float tv[40];
; #pragma unroll
;         for (int kt = 0; kt < 10; ++kt)
; #pragma unroll
;             for (int jj = 0; jj < 4; ++jj) tv[4 * kt + jj] = tb[159 - (32 * (kt >> 1) + 4 * (kt & 1) + jj)];
;         SBAR();
;         float mx = NEGF;
; #pragma unroll
;         for (int kt = 0; kt < 10; ++kt)
; #pragma unroll
;             for (int jj = 0; jj < 4; ++jj) {
;                 const int c = 32 * (kt >> 1) + 4 * (kt & 1) + jj;
;                 float v = S[kt][jj] * 0.125f + tv[4 * kt + jj];
;                 if ((kt >> 1) == 0) v = (L - c <= 128) ? v : NEGF;
;                 if ((kt >> 1) == 4) v = (L - c >= 0) ? v : NEGF;
;                 S[kt][jj] = v;
;             }
	s_waitcnt vmcnt(31)
	v_mfma_f32_16x16x32_bf16 v[166:169], v[178:181], v[84:87], 0
	v_cndmask_b32_e64 v148, v237, v151, s[50:51]
	v_cndmask_b32_e64 v151, v237, v150, s[44:45]
	v_fmamk_f32 v150, v156, 0x3e000000, v185
	v_mfma_f32_16x16x32_bf16 v[162:165], v[174:177], v[80:83], v[162:165]
	v_cndmask_b32_e64 v152, v237, v152, s[42:43]
	v_cndmask_b32_e64 v150, v237, v150, s[48:49]
	s_waitcnt vmcnt(30)
	v_mfma_f32_16x16x32_bf16 v[154:157], v[128:131], v[80:83], v[166:169]
	ds_read2_b32 v[130:131], v186 offset0:143 offset1:144
	ds_read2_b32 v[170:171], v186 offset0:141 offset1:142
	ds_read2_b32 v[172:173], v186 offset0:139 offset1:140
	ds_read2_b32 v[174:175], v186 offset0:137 offset1:138
	v_cndmask_b32_e64 v128, v237, v184, s[52:53]
	s_waitcnt vmcnt(29)
	v_mfma_f32_16x16x32_bf16 v[166:169], v[124:127], v[84:87], 0
	s_waitcnt lgkmcnt(3)
	v_pk_fma_f32 v[126:127], v[158:159], s[80:81], v[130:131] op_sel:[0,0,1] op_sel_hi:[1,0,0]
	s_waitcnt lgkmcnt(2)
	v_pk_fma_f32 v[124:125], v[160:161], s[80:81], v[170:171] op_sel:[0,0,1] op_sel_hi:[1,0,0]
	ds_read2_b32 v[130:131], v186 offset0:111 offset1:112
	s_waitcnt vmcnt(28)
	v_mfma_f32_16x16x32_bf16 v[158:161], v[120:123], v[80:83], v[166:169]
	s_waitcnt lgkmcnt(2)
	v_pk_fma_f32 v[122:123], v[162:163], s[80:81], v[172:173] op_sel:[0,0,1] op_sel_hi:[1,0,0]
	s_waitcnt lgkmcnt(1)
	v_pk_fma_f32 v[120:121], v[164:165], s[80:81], v[174:175] op_sel:[0,0,1] op_sel_hi:[1,0,0]
	s_waitcnt vmcnt(20)
	ds_write_b128 v206, v[104:107] offset:2240
	ds_write_b128 v206, v[96:99] offset:2816
	ds_write_b128 v206, v[92:95] offset:3392
	ds_write_b128 v206, v[88:91] offset:3968
	ds_read_b128 v[104:107], v207 offset:2240
	ds_read_b128 v[96:99], v207 offset:2304
	ds_read_b128 v[92:95], v207 offset:4544
	ds_read_b128 v[88:91], v207 offset:4608
	s_waitcnt lgkmcnt(8)
	s_waitcnt vmcnt(27)
	v_mfma_f32_16x16x32_bf16 v[162:165], v[116:119], v[84:87], 0
	ds_read2_b32 v[116:117], v186 offset0:109 offset1:110
	ds_read2_b32 v[166:167], v186 offset0:107 offset1:108
	ds_read2_b32 v[168:169], v186 offset0:105 offset1:106
	s_waitcnt lgkmcnt(3)
	v_pk_fma_f32 v[118:119], v[154:155], s[80:81], v[130:131] op_sel:[0,0,1] op_sel_hi:[1,0,0]
	s_waitcnt lgkmcnt(2)
	v_pk_fma_f32 v[116:117], v[156:157], s[80:81], v[116:117] op_sel:[0,0,1] op_sel_hi:[1,0,0]
	s_waitcnt vmcnt(25)
	v_mfma_f32_16x16x32_bf16 v[108:111], v[108:111], v[84:87], 0
	v_mfma_f32_16x16x32_bf16 v[162:165], v[112:115], v[80:83], v[162:165]
	s_waitcnt lgkmcnt(1)
	v_pk_fma_f32 v[114:115], v[158:159], s[80:81], v[166:167] op_sel:[0,0,1] op_sel_hi:[1,0,0]
	s_waitcnt lgkmcnt(0)
	v_pk_fma_f32 v[112:113], v[160:161], s[80:81], v[168:169] op_sel:[0,0,1] op_sel_hi:[1,0,0]
	ds_read2_b32 v[130:131], v186 offset0:79 offset1:80
	ds_read2_b32 v[158:159], v186 offset0:77 offset1:78
	ds_read2_b32 v[160:161], v186 offset0:75 offset1:76
	ds_read2_b32 v[166:167], v186 offset0:73 offset1:74
	s_waitcnt vmcnt(24)
	v_mfma_f32_16x16x32_bf16 v[154:157], v[100:103], v[80:83], v[108:111]
	s_waitcnt lgkmcnt(0)
	s_waitcnt vmcnt(23)
	v_mfma_f32_16x16x32_bf16 v[104:107], v[104:107], v[84:87], 0
	s_waitcnt lgkmcnt(3)
	v_pk_fma_f32 v[110:111], v[162:163], s[80:81], v[130:131] op_sel:[0,0,1] op_sel_hi:[1,0,0]
	s_waitcnt lgkmcnt(1)
	s_nop 2
	v_pk_fma_f32 v[102:103], v[154:155], s[80:81], v[160:161] op_sel:[0,0,1] op_sel_hi:[1,0,0]
	ds_read2_b32 v[130:131], v186 offset0:47 offset1:48
	ds_read2_b32 v[154:155], v186 offset0:45 offset1:46
	s_waitcnt vmcnt(22)
	v_mfma_f32_16x16x32_bf16 v[96:99], v[96:99], v[80:83], v[104:107]
	v_fma_f32 v108, v164, s80, v159
	v_fma_f32 v109, v165, s80, v158
	s_waitcnt lgkmcnt(2)
	v_pk_fma_f32 v[100:101], v[156:157], s[80:81], v[166:167] op_sel:[0,0,1] op_sel_hi:[1,0,0]
	s_waitcnt vmcnt(21)
	v_mfma_f32_16x16x32_bf16 v[92:95], v[92:95], v[84:87], 0
	s_waitcnt vmcnt(20)
	v_mfma_f32_16x16x32_bf16 v[86:89], v[88:91], v[80:83], v[92:95]
	s_waitcnt lgkmcnt(1)
	v_pk_fma_f32 v[104:105], v[96:97], s[80:81], v[130:131] op_sel:[0,0,1] op_sel_hi:[1,0,0]
	s_waitcnt lgkmcnt(0)
	v_pk_fma_f32 v[98:99], v[98:99], s[80:81], v[154:155] op_sel:[0,0,1] op_sel_hi:[1,0,0]
	v_cndmask_b32_e64 v96, v105, v237, s[38:39]
	v_cndmask_b32_e64 v97, v104, v237, s[54:55]
	ds_read2_b32 v[104:105], v186 offset0:43 offset1:44
	v_cndmask_b32_e64 v84, v99, v237, s[40:41]
	v_cndmask_b32_e64 v85, v98, v237, s[42:43]
	ds_read2_b32 v[98:99], v186 offset0:41 offset1:42
	s_waitcnt lgkmcnt(1)
	v_pk_fma_f32 v[80:81], v[86:87], s[80:81], v[104:105] op_sel:[0,0,1] op_sel_hi:[1,0,0]
	s_nop 0
	v_cndmask_b32_e64 v82, v81, v237, s[44:45]
	v_cndmask_b32_e64 v83, v80, v237, s[46:47]
	s_waitcnt lgkmcnt(0)
	v_pk_fma_f32 v[86:87], v[88:89], s[80:81], v[98:99] op_sel:[0,0,1] op_sel_hi:[1,0,0]
	s_cmpk_gt_i32 s24, 0x8f
	v_cndmask_b32_e64 v80, v87, v237, s[48:49]
	v_cndmask_b32_e64 v86, v86, v237, s[50:51]
	s_cbranch_scc1 .LBB0_567
; __device__ __forceinline__ void attnA_unit(const Ctx& C, int unit) {
;     ...
;         if (anyneg) {
; #pragma unroll
;             for (int kt = 0; kt < 10; ++kt)
; #pragma unroll
;                 for (int jj = 0; jj < 4; ++jj) { const int c = 32 * (kt >> 1) + 4 * (kt & 1) + jj; S[kt][jj] = (kneg + c >= 0) ? S[kt][jj] : NEGF; }
;         }
	v_add_u32_e32 v81, s25, v134
	v_cmp_lt_i32_e64 s[56:57], -1, v81
	s_movk_i32 s24, 0xffdf
	s_nop 0
	v_cndmask_b32_e64 v146, v237, v146, s[56:57]
	v_cmp_lt_i32_e64 s[56:57], -2, v81
	s_nop 1
	v_cndmask_b32_e64 v152, v237, v152, s[56:57]
	v_cmp_lt_i32_e64 s[56:57], -3, v81
	s_nop 1
	v_cndmask_b32_e64 v147, v237, v147, s[56:57]
	v_cmp_lt_i32_e64 s[56:57], -4, v81
	s_nop 1
	v_cndmask_b32_e64 v149, v237, v149, s[56:57]
	v_cmp_lt_i32_e64 s[56:57], -5, v81
	s_nop 1
	v_cndmask_b32_e64 v151, v237, v151, s[56:57]
	v_cmp_lt_i32_e64 s[56:57], -6, v81
	s_nop 1
	v_cndmask_b32_e64 v148, v237, v148, s[56:57]
	v_cmp_lt_i32_e64 s[56:57], -7, v81
	s_nop 1
	v_cndmask_b32_e64 v150, v237, v150, s[56:57]
	v_cmp_lt_i32_e64 s[56:57], -8, v81
	s_nop 1
	v_cndmask_b32_e64 v128, v237, v128, s[56:57]
	v_cmp_lt_i32_e64 s[56:57], s24, v81
	s_movk_i32 s24, 0xffde
	s_nop 0
	v_cndmask_b32_e64 v126, v237, v126, s[56:57]
	v_cmp_lt_i32_e64 s[56:57], s24, v81
	s_movk_i32 s24, 0xffdd
	s_nop 0
	v_cndmask_b32_e64 v127, v237, v127, s[56:57]
	v_cmp_lt_i32_e64 s[56:57], s24, v81
	s_movk_i32 s24, 0xffdc
	s_nop 0
	v_cndmask_b32_e64 v124, v237, v124, s[56:57]
	v_cmp_lt_i32_e64 s[56:57], s24, v81
	s_movk_i32 s24, 0xffdb
	s_nop 0
	v_cndmask_b32_e64 v125, v237, v125, s[56:57]
	v_cmp_lt_i32_e64 s[56:57], s24, v81
	s_movk_i32 s24, 0xffda
	s_nop 0
	v_cndmask_b32_e64 v122, v237, v122, s[56:57]
	v_cmp_lt_i32_e64 s[56:57], s24, v81
	s_movk_i32 s24, 0xffd9
	s_nop 0
	v_cndmask_b32_e64 v123, v237, v123, s[56:57]
	v_cmp_lt_i32_e64 s[56:57], s24, v81
	s_movk_i32 s24, 0xffd8
	s_nop 0
	v_cndmask_b32_e64 v120, v237, v120, s[56:57]
	v_cmp_lt_i32_e64 s[56:57], s24, v81
	s_movk_i32 s24, 0xffbf
	s_nop 0
	v_cndmask_b32_e64 v121, v237, v121, s[56:57]
	v_cmp_lt_i32_e64 s[56:57], s24, v81
	s_movk_i32 s24, 0xffbe
	s_nop 0
	v_cndmask_b32_e64 v118, v237, v118, s[56:57]
	v_cmp_lt_i32_e64 s[56:57], s24, v81
	s_movk_i32 s24, 0xffbd
	s_nop 0
	v_cndmask_b32_e64 v119, v237, v119, s[56:57]
	v_cmp_lt_i32_e64 s[56:57], s24, v81
	s_movk_i32 s24, 0xffbc
	s_nop 0
	v_cndmask_b32_e64 v116, v237, v116, s[56:57]
	v_cmp_lt_i32_e64 s[56:57], s24, v81
	s_movk_i32 s24, 0xffbb
	s_nop 0
	v_cndmask_b32_e64 v117, v237, v117, s[56:57]
	v_cmp_lt_i32_e64 s[56:57], s24, v81
	s_movk_i32 s24, 0xffba
	s_nop 0
	v_cndmask_b32_e64 v114, v237, v114, s[56:57]
	v_cmp_lt_i32_e64 s[56:57], s24, v81
	s_movk_i32 s24, 0xffb9
	s_nop 0
	v_cndmask_b32_e64 v115, v237, v115, s[56:57]
	v_cmp_lt_i32_e64 s[56:57], s24, v81
	s_movk_i32 s24, 0xffb8
	s_nop 0
	v_cndmask_b32_e64 v112, v237, v112, s[56:57]
	v_cmp_lt_i32_e64 s[56:57], s24, v81
	s_movk_i32 s24, 0xff9f
	s_nop 0
	v_cndmask_b32_e64 v113, v237, v113, s[56:57]
	v_cmp_lt_i32_e64 s[56:57], s24, v81
	s_movk_i32 s24, 0xff9e
	s_nop 0
	v_cndmask_b32_e64 v110, v237, v110, s[56:57]
	v_cmp_lt_i32_e64 s[56:57], s24, v81
	s_movk_i32 s24, 0xff9d
	s_nop 0
	v_cndmask_b32_e64 v111, v237, v111, s[56:57]
	v_cmp_lt_i32_e64 s[56:57], s24, v81
	s_movk_i32 s24, 0xff9c
	s_nop 0
	v_cndmask_b32_e64 v108, v237, v108, s[56:57]
	v_cmp_lt_i32_e64 s[56:57], s24, v81
	s_movk_i32 s24, 0xff9b
	s_nop 0
	v_cndmask_b32_e64 v109, v237, v109, s[56:57]
	v_cmp_lt_i32_e64 s[56:57], s24, v81
	s_movk_i32 s24, 0xff9a
	s_nop 0
	v_cndmask_b32_e64 v102, v237, v102, s[56:57]
	v_cmp_lt_i32_e64 s[56:57], s24, v81
	s_movk_i32 s24, 0xff99
	s_nop 0
	v_cndmask_b32_e64 v103, v237, v103, s[56:57]
	v_cmp_lt_i32_e64 s[56:57], s24, v81
	s_movk_i32 s24, 0xff98
	s_nop 0
	v_cndmask_b32_e64 v100, v237, v100, s[56:57]
	v_cmp_lt_i32_e64 s[56:57], s24, v81
	s_movk_i32 s24, 0xff7f
	s_nop 0
	v_cndmask_b32_e64 v101, v237, v101, s[56:57]
	v_cmp_lt_i32_e64 s[56:57], s24, v81
	s_movk_i32 s24, 0xff7e
	s_nop 0
	v_cndmask_b32_e64 v97, v237, v97, s[56:57]
	v_cmp_lt_i32_e64 s[56:57], s24, v81
	s_movk_i32 s24, 0xff7d
	s_nop 0
	v_cndmask_b32_e64 v96, v237, v96, s[56:57]
	v_cmp_lt_i32_e64 s[56:57], s24, v81
	s_movk_i32 s24, 0xff7b
	s_nop 0
	v_cndmask_b32_e64 v85, v237, v85, s[56:57]
	v_cmp_lt_i32_e64 s[56:57], s6, v81
	s_nop 1
	v_cndmask_b32_e64 v84, v237, v84, s[56:57]
	v_cmp_lt_i32_e64 s[56:57], s24, v81
	s_movk_i32 s24, 0xff7a
	s_nop 0
	v_cndmask_b32_e64 v83, v237, v83, s[56:57]
	v_cmp_lt_i32_e64 s[56:57], s24, v81
	s_movk_i32 s24, 0xff79
	s_nop 0
	v_cndmask_b32_e64 v82, v237, v82, s[56:57]
	v_cmp_lt_i32_e64 s[56:57], s24, v81
	s_movk_i32 s24, 0xff78
	s_nop 0
	v_cndmask_b32_e64 v86, v237, v86, s[56:57]
	v_cmp_lt_i32_e64 s[56:57], s24, v81
	s_nop 1
	v_cndmask_b32_e64 v80, v237, v80, s[56:57]
